# mixer queue: retention output items interleaved 1:2 with attention items so the queue ends with small items
# baseline (speedup 1.0000x reference)
.LBB0_312:
	s_or_b64 exec, exec, s[0:1]
	s_add_i32 s0, 0, 0x20000
	v_readlane_b32 s6, v253, 7
	s_cmp_lg_u32 s0, -1
	v_readlane_b32 s7, v253, 8
	s_cselect_b32 s0, s0, 0
	s_cselect_b32 s1, s7, 0
	s_waitcnt vmcnt(0)
	v_mov_b32_e32 v2, s0
	v_mov_b32_e32 v3, s1
	s_waitcnt lgkmcnt(0)
	s_barrier
	flat_load_dword v0, v[2:3] sc0 sc1
	s_waitcnt vmcnt(0)
	s_mov_b64 s[0:1], -1
	s_waitcnt lgkmcnt(0)
	s_barrier
	v_readfirstlane_b32 s76, v0
	s_cmp_ge_i32 s76, s75
	s_cbranch_scc1 .LBB0_307
	s_cmp_lt_u32 s76, 96
	s_cbranch_scc1 .Lq_done
	s_sub_i32 s100, s76, 96
	s_cmp_lt_u32 s100, 204
	s_cbranch_scc0 .Lq_tail
	s_mul_hi_u32 s101, s100, 0xaaaaaaab
	s_lshr_b32 s101, s101, 1
	s_mul_i32 s76, s101, 3
	s_sub_i32 s100, s100, s76
	s_cmp_lt_u32 s100, 2
	s_cbranch_scc0 .Lq_retc
	s_lshl_b32 s76, s101, 1
	s_add_i32 s76, s76, s100
	s_add_i32 s76, s76, 96
	s_branch .Lq_done

.Lq_tail:
	s_add_i32 s76, s100, 28
